# attention QK MFMA order: alternate the two score accumulators so every consecutive pair shares the Q operand or chains the accumulator
# speedup vs baseline: 1.0108x; 1.0108x over previous
.LBB0_243:
	s_cmp_gt_i32 s26, s52
	s_cbranch_scc1 .LBB0_236
	s_mul_hi_u32 s26, s55, 0xaaaaaaab
	s_lshr_b32 s26, s26, 1
	s_mul_i32 s26, s26, 0x18000
	v_subrev_u32_e32 v72, s26, v179
	v_subrev_u32_e32 v73, s26, v177
	v_subrev_u32_e32 v74, s26, v175
	v_subrev_u32_e32 v64, s26, v173
	v_add_u32_e32 v75, s54, v182
	v_add_u32_e32 v68, v75, v64
	v_add_u32_e32 v74, v75, v74
	v_add_u32_e32 v73, v75, v73
	v_add_u32_e32 v72, v75, v72
	ds_read_b128 v[64:67], v68
	ds_read_b128 v[68:71], v68 offset:8192
	ds_read_b128 v[188:191], v74
	ds_read_b128 v[192:195], v74 offset:8192
	ds_read_b128 v[196:199], v73
	ds_read_b128 v[200:203], v73 offset:8192
	ds_read_b128 v[208:211], v72
	ds_read_b128 v[214:217], v72 offset:8192
	s_waitcnt lgkmcnt(0)
	s_setprio 1
	s_waitcnt lgkmcnt(0)
	v_mfma_f32_32x32x16_bf16 v[80:95], v[64:67], v[96:99], 0
	v_mfma_f32_32x32x16_bf16 v[64:79], v[68:71], v[96:99], 0
	v_mfma_f32_32x32x16_bf16 v[64:79], v[192:195], v[100:103], v[64:79]
	v_mfma_f32_32x32x16_bf16 v[80:95], v[188:191], v[100:103], v[80:95]
	v_mfma_f32_32x32x16_bf16 v[80:95], v[196:199], v[104:107], v[80:95]
	v_mfma_f32_32x32x16_bf16 v[64:79], v[200:203], v[104:107], v[64:79]
	v_mfma_f32_32x32x16_bf16 v[64:79], v[214:217], v[108:111], v[64:79]
	v_mfma_f32_32x32x16_bf16 v[80:95], v[208:211], v[108:111], v[80:95]
	s_setprio 0
	s_nop 10
	v_max3_f32 v147, v80, v81, v82
	v_max3_f32 v149, v64, v65, v66
	v_max3_f32 v147, v147, v83, v84
	v_max3_f32 v149, v149, v67, v68
	v_max3_f32 v147, v147, v85, v86
	v_max3_f32 v149, v149, v69, v70
	v_max3_f32 v147, v147, v87, v88
	v_max3_f32 v149, v149, v71, v72
	v_max3_f32 v147, v147, v89, v90
	v_max3_f32 v149, v149, v73, v74
	v_max3_f32 v147, v147, v91, v92
	v_max3_f32 v149, v149, v75, v76
	v_max3_f32 v147, v147, v93, v94
	v_max3_f32 v149, v149, v77, v78
	v_max3_f32 v147, v147, v95, v79
	v_max_f32_e32 v147, v147, v149
	v_mov_b32_e32 v149, v147
	s_nop 1
	v_permlane32_swap_b32_e32 v147, v149
	v_max_f32_e32 v149, v149, v149
	v_max_f32_e32 v147, v147, v147
	v_max_f32_e32 v147, v147, v149
	v_cmp_gt_f32_e32 vcc, v147, v145
	s_cbranch_vccz .LBB0_235
	v_max_f32_e32 v147, v147, v147
	v_max_f32_e32 v149, v145, v145
	v_max_f32_e32 v147, v149, v147
	v_sub_f32_e32 v145, v145, v147
	v_exp_f32_e32 v188, v145
	v_mov_b32_e32 v145, v147
	v_pk_mul_f32 v[62:63], v[62:63], v[188:189] op_sel_hi:[1,0]
	v_pk_mul_f32 v[60:61], v[60:61], v[188:189] op_sel_hi:[1,0]
	v_pk_mul_f32 v[58:59], v[58:59], v[188:189] op_sel_hi:[1,0]
	v_pk_mul_f32 v[56:57], v[56:57], v[188:189] op_sel_hi:[1,0]
	v_pk_mul_f32 v[54:55], v[54:55], v[188:189] op_sel_hi:[1,0]
	v_pk_mul_f32 v[52:53], v[52:53], v[188:189] op_sel_hi:[1,0]
	v_pk_mul_f32 v[50:51], v[50:51], v[188:189] op_sel_hi:[1,0]
	v_pk_mul_f32 v[48:49], v[48:49], v[188:189] op_sel_hi:[1,0]
	v_pk_mul_f32 v[46:47], v[46:47], v[188:189] op_sel_hi:[1,0]
	v_pk_mul_f32 v[44:45], v[44:45], v[188:189] op_sel_hi:[1,0]
	v_pk_mul_f32 v[42:43], v[42:43], v[188:189] op_sel_hi:[1,0]
	v_pk_mul_f32 v[40:41], v[40:41], v[188:189] op_sel_hi:[1,0]
	v_pk_mul_f32 v[38:39], v[38:39], v[188:189] op_sel_hi:[1,0]
	v_pk_mul_f32 v[36:37], v[36:37], v[188:189] op_sel_hi:[1,0]
	v_pk_mul_f32 v[34:35], v[34:35], v[188:189] op_sel_hi:[1,0]
	v_pk_mul_f32 v[32:33], v[32:33], v[188:189] op_sel_hi:[1,0]
	v_pk_mul_f32 v[30:31], v[30:31], v[188:189] op_sel_hi:[1,0]
	v_pk_mul_f32 v[28:29], v[28:29], v[188:189] op_sel_hi:[1,0]
	v_pk_mul_f32 v[26:27], v[26:27], v[188:189] op_sel_hi:[1,0]
	v_pk_mul_f32 v[24:25], v[24:25], v[188:189] op_sel_hi:[1,0]
	v_pk_mul_f32 v[22:23], v[22:23], v[188:189] op_sel_hi:[1,0]
	v_pk_mul_f32 v[20:21], v[20:21], v[188:189] op_sel_hi:[1,0]
	v_pk_mul_f32 v[18:19], v[18:19], v[188:189] op_sel_hi:[1,0]
	v_pk_mul_f32 v[16:17], v[16:17], v[188:189] op_sel_hi:[1,0]
	v_pk_mul_f32 v[14:15], v[14:15], v[188:189] op_sel_hi:[1,0]
	v_pk_mul_f32 v[12:13], v[12:13], v[188:189] op_sel_hi:[1,0]
	v_pk_mul_f32 v[10:11], v[10:11], v[188:189] op_sel_hi:[1,0]
	v_pk_mul_f32 v[8:9], v[8:9], v[188:189] op_sel_hi:[1,0]
	v_pk_mul_f32 v[6:7], v[6:7], v[188:189] op_sel_hi:[1,0]
	v_pk_mul_f32 v[4:5], v[4:5], v[188:189] op_sel_hi:[1,0]
	v_pk_mul_f32 v[2:3], v[2:3], v[188:189] op_sel_hi:[1,0]
	v_pk_mul_f32 v[0:1], v[0:1], v[188:189] op_sel_hi:[1,0]
	v_mul_f32_e32 v143, v143, v188
	s_branch .LBB0_235
